# P5 hgrn_out: the four serialised global->LDS copies of S_prev (load, vmcnt(0), ds_write x4) issue all loads back to back into distinct registers with one wait
# speedup vs baseline: 1.0184x; 1.0025x over previous
.LBB0_1443:
	s_or_b64 exec, exec, s[6:7]
	v_readlane_b32 s2, v253, 21
	v_readlane_b32 s3, v253, 22
	v_lshlrev_b32_e32 v2, 4, v43
	v_and_b32_e32 v166, 0xf0, v2
	s_waitcnt vmcnt(0)
	v_lshl_add_u64 v[0:1], v[16:17], 0, s[2:3]
	v_lshl_add_u64 v[0:1], v[0:1], 0, v[166:167]
	s_mov_b64 s[2:3], 0x264c2800
	v_ashrrev_i32_e32 v7, 4, v43
	v_lshl_add_u64 v[4:5], v[0:1], 0, s[2:3]
	v_lshlrev_b32_e32 v0, 7, v7
	v_ashrrev_i32_e32 v1, 31, v0
	v_lshl_add_u64 v[0:1], v[0:1], 1, v[4:5]
	s_waitcnt lgkmcnt(0)
	s_barrier
	global_load_dwordx4 v[12:15], v[0:1], off
	v_add_u32_e32 v6, 0, v166
	v_mad_u64_u32 v[100:101], s[6:7], v7, s50, v[6:7]
	v_lshlrev_b32_e32 v11, 4, v22
	v_readlane_b32 s2, v254, 45
	v_add_u32_e32 v0, 0x200, v43
	v_ashrrev_i32_e32 v7, 4, v0
	v_lshlrev_b32_e32 v0, 7, v7
	v_ashrrev_i32_e32 v1, 31, v0
	v_lshl_add_u64 v[0:1], v[0:1], 1, v[4:5]
	global_load_dwordx4 v[56:59], v[0:1], off
	v_mad_u64_u32 v[102:103], s[6:7], v7, s50, v[6:7]
	v_add_u32_e32 v0, 0x400, v43
	v_ashrrev_i32_e32 v7, 4, v0
	v_lshlrev_b32_e32 v0, 7, v7
	v_ashrrev_i32_e32 v1, 31, v0
	v_lshl_add_u64 v[0:1], v[0:1], 1, v[4:5]
	global_load_dwordx4 v[60:63], v[0:1], off
	v_mad_u64_u32 v[104:105], s[6:7], v7, s50, v[6:7]
	v_add_u32_e32 v0, 0x600, v43
	v_ashrrev_i32_e32 v7, 4, v0
	v_lshlrev_b32_e32 v0, 7, v7
	v_ashrrev_i32_e32 v1, 31, v0
	v_lshl_add_u64 v[0:1], v[0:1], 1, v[4:5]
	global_load_dwordx4 v[96:99], v[0:1], off
	v_mad_u64_u32 v[4:5], s[6:7], v7, s50, v[6:7]
	v_and_b32_e32 v7, 15, v43
	v_mov_b32_e32 v5, 0
	s_waitcnt vmcnt(0)
	ds_write_b128 v100, v[12:15]
	ds_write_b128 v102, v[56:59]
	ds_write_b128 v104, v[60:63]
	ds_write_b128 v4, v[96:99]
	v_lshlrev_b32_e32 v0, 1, v40
	v_and_b32_e32 v1, 2, v0
	v_mad_u64_u32 v[2:3], s[6:7], v22, v22, v[22:23]
	v_or_b32_e32 v0, v11, v7
	v_mul_lo_u32 v0, v0, s50
	v_and_b32_e32 v3, 48, v45
	v_add3_u32 v8, 0, v0, v3
	v_lshl_add_u32 v9, v2, 3, v7
	v_add_u32_e32 v6, s2, v3
	v_cmp_gt_i32_e32 vcc, v1, v22
	v_cmp_le_i32_e64 s[8:9], v1, v22
	v_lshlrev_b32_e32 v10, 4, v1
	v_mov_b32_e32 v0, 0
	v_mov_b32_e32 v2, 0
	v_mov_b32_e32 v3, 0
	v_mov_b32_e32 v4, 0
	s_and_saveexec_b64 s[6:7], s[8:9]
	s_cbranch_execz .LBB0_1445
	v_add_u32_e32 v2, v9, v10
	v_mad_u64_u32 v[60:61], s[8:9], v2, s50, v[6:7]
	ds_read_b128 v[2:5], v8 offset:34816
	ds_read_b128 v[12:15], v60
	s_waitcnt lgkmcnt(0)
	v_mfma_f32_16x16x32_bf16 v[2:5], v[2:5], v[12:15], 0
	ds_read_b128 v[12:15], v8 offset:34880
	ds_read_b128 v[56:59], v60 offset:64
	s_waitcnt lgkmcnt(0)
	v_mfma_f32_16x16x32_bf16 v[2:5], v[12:15], v[56:59], v[2:5]
	ds_read_b128 v[12:15], v8 offset:34944
	ds_read_b128 v[56:59], v60 offset:128
	s_waitcnt lgkmcnt(0)
	v_mfma_f32_16x16x32_bf16 v[2:5], v[12:15], v[56:59], v[2:5]
	ds_read_b128 v[12:15], v8 offset:35008
	ds_read_b128 v[56:59], v60 offset:192
	s_waitcnt lgkmcnt(0)
	v_mfma_f32_16x16x32_bf16 v[2:5], v[12:15], v[56:59], v[2:5]

.LBB0_1511:
	s_or_b64 exec, exec, s[6:7]
	v_readlane_b32 s2, v253, 26
	v_readlane_b32 s3, v253, 27
	v_lshlrev_b32_e32 v2, 4, v97
	v_and_b32_e32 v166, 0xf0, v2
	s_waitcnt vmcnt(0)
	v_lshl_add_u64 v[0:1], v[20:21], 0, s[2:3]
	v_lshl_add_u64 v[0:1], v[0:1], 0, v[166:167]
	s_mov_b64 s[2:3], 0x264c2800
	v_ashrrev_i32_e32 v7, 4, v97
	v_lshl_add_u64 v[4:5], v[0:1], 0, s[2:3]
	v_lshlrev_b32_e32 v0, 7, v7
	v_ashrrev_i32_e32 v1, 31, v0
	v_lshl_add_u64 v[0:1], v[0:1], 1, v[4:5]
	s_waitcnt lgkmcnt(0)
	s_barrier
	global_load_dwordx4 v[100:103], v[0:1], off
	v_add_u32_e32 v6, 0, v166
	v_mad_u64_u32 v[136:137], s[6:7], v7, s50, v[6:7]
	v_lshlrev_b32_e32 v12, 4, v18
	v_readlane_b32 s2, v254, 45
	v_add_u32_e32 v0, 0x200, v97
	v_ashrrev_i32_e32 v7, 4, v0
	v_lshlrev_b32_e32 v0, 7, v7
	v_ashrrev_i32_e32 v1, 31, v0
	v_lshl_add_u64 v[0:1], v[0:1], 1, v[4:5]
	global_load_dwordx4 v[104:107], v[0:1], off
	v_mad_u64_u32 v[138:139], s[6:7], v7, s50, v[6:7]
	v_add_u32_e32 v0, 0x400, v97
	v_ashrrev_i32_e32 v7, 4, v0
	v_lshlrev_b32_e32 v0, 7, v7
	v_ashrrev_i32_e32 v1, 31, v0
	v_lshl_add_u64 v[0:1], v[0:1], 1, v[4:5]
	global_load_dwordx4 v[108:111], v[0:1], off
	v_mad_u64_u32 v[140:141], s[6:7], v7, s50, v[6:7]
	v_add_u32_e32 v0, 0x600, v97
	v_ashrrev_i32_e32 v7, 4, v0
	v_lshlrev_b32_e32 v0, 7, v7
	v_ashrrev_i32_e32 v1, 31, v0
	v_lshl_add_u64 v[0:1], v[0:1], 1, v[4:5]
	global_load_dwordx4 v[132:135], v[0:1], off
	v_mad_u64_u32 v[4:5], s[6:7], v7, s50, v[6:7]
	v_and_b32_e32 v7, 15, v97
	v_mov_b32_e32 v5, 0
	s_waitcnt vmcnt(0)
	ds_write_b128 v136, v[100:103]
	ds_write_b128 v138, v[104:107]
	ds_write_b128 v140, v[108:111]
	ds_write_b128 v4, v[132:135]
	v_lshlrev_b32_e32 v0, 1, v95
	v_and_b32_e32 v1, 2, v0
	v_mad_u64_u32 v[2:3], s[6:7], v18, v18, v[18:19]
	v_or_b32_e32 v0, v12, v7
	v_mul_lo_u32 v0, v0, s50
	v_and_b32_e32 v3, 48, v11
	v_add3_u32 v8, 0, v0, v3
	v_lshl_add_u32 v9, v2, 3, v7
	v_add_u32_e32 v6, s2, v3
	v_cmp_gt_i32_e32 vcc, v1, v18
	v_cmp_le_i32_e64 s[8:9], v1, v18
	v_lshlrev_b32_e32 v10, 4, v1
	v_mov_b32_e32 v0, 0
	v_mov_b32_e32 v2, 0
	v_mov_b32_e32 v3, 0
	v_mov_b32_e32 v4, 0
	s_and_saveexec_b64 s[6:7], s[8:9]
	s_cbranch_execz .LBB0_1513
	v_add_u32_e32 v2, v9, v10
	v_mad_u64_u32 v[14:15], s[8:9], v2, s50, v[6:7]
	ds_read_b128 v[2:5], v8 offset:34816
	ds_read_b128 v[98:101], v14
	s_waitcnt lgkmcnt(0)
	v_mfma_f32_16x16x32_bf16 v[2:5], v[2:5], v[98:101], 0
	ds_read_b128 v[98:101], v8 offset:34880
	ds_read_b128 v[102:105], v14 offset:64
	s_waitcnt lgkmcnt(0)
	v_mfma_f32_16x16x32_bf16 v[2:5], v[98:101], v[102:105], v[2:5]
	ds_read_b128 v[98:101], v8 offset:34944
	ds_read_b128 v[102:105], v14 offset:128
	s_waitcnt lgkmcnt(0)
	v_mfma_f32_16x16x32_bf16 v[2:5], v[98:101], v[102:105], v[2:5]
	ds_read_b128 v[98:101], v8 offset:35008
	ds_read_b128 v[102:105], v14 offset:192
	s_waitcnt lgkmcnt(0)
	v_mfma_f32_16x16x32_bf16 v[2:5], v[98:101], v[102:105], v[2:5]

.LBB0_1579:
	s_or_b64 exec, exec, s[6:7]
	v_readlane_b32 s2, v253, 31
	v_readlane_b32 s3, v253, 32
	v_lshlrev_b32_e32 v2, 4, v97
	v_and_b32_e32 v166, 0xf0, v2
	s_waitcnt vmcnt(0)
	v_lshl_add_u64 v[0:1], v[20:21], 0, s[2:3]
	v_lshl_add_u64 v[0:1], v[0:1], 0, v[166:167]
	s_mov_b64 s[2:3], 0x264c2800
	v_ashrrev_i32_e32 v7, 4, v97
	v_lshl_add_u64 v[4:5], v[0:1], 0, s[2:3]
	v_lshlrev_b32_e32 v0, 7, v7
	v_ashrrev_i32_e32 v1, 31, v0
	v_lshl_add_u64 v[0:1], v[0:1], 1, v[4:5]
	s_waitcnt lgkmcnt(0)
	s_barrier
	global_load_dwordx4 v[100:103], v[0:1], off
	v_add_u32_e32 v6, 0, v166
	v_mad_u64_u32 v[136:137], s[6:7], v7, s50, v[6:7]
	v_lshlrev_b32_e32 v12, 4, v16
	v_readlane_b32 s2, v254, 45
	v_add_u32_e32 v0, 0x200, v97
	v_ashrrev_i32_e32 v7, 4, v0
	v_lshlrev_b32_e32 v0, 7, v7
	v_ashrrev_i32_e32 v1, 31, v0
	v_lshl_add_u64 v[0:1], v[0:1], 1, v[4:5]
	global_load_dwordx4 v[104:107], v[0:1], off
	v_mad_u64_u32 v[138:139], s[6:7], v7, s50, v[6:7]
	v_add_u32_e32 v0, 0x400, v97
	v_ashrrev_i32_e32 v7, 4, v0
	v_lshlrev_b32_e32 v0, 7, v7
	v_ashrrev_i32_e32 v1, 31, v0
	v_lshl_add_u64 v[0:1], v[0:1], 1, v[4:5]
	global_load_dwordx4 v[108:111], v[0:1], off
	v_mad_u64_u32 v[140:141], s[6:7], v7, s50, v[6:7]
	v_add_u32_e32 v0, 0x600, v97
	v_ashrrev_i32_e32 v7, 4, v0
	v_lshlrev_b32_e32 v0, 7, v7
	v_ashrrev_i32_e32 v1, 31, v0
	v_lshl_add_u64 v[0:1], v[0:1], 1, v[4:5]
	global_load_dwordx4 v[132:135], v[0:1], off
	v_mad_u64_u32 v[4:5], s[6:7], v7, s50, v[6:7]
	v_and_b32_e32 v7, 15, v97
	v_mov_b32_e32 v5, 0
	s_waitcnt vmcnt(0)
	ds_write_b128 v136, v[100:103]
	ds_write_b128 v138, v[104:107]
	ds_write_b128 v140, v[108:111]
	ds_write_b128 v4, v[132:135]
	v_lshlrev_b32_e32 v0, 1, v95
	v_and_b32_e32 v1, 2, v0
	v_mad_u64_u32 v[2:3], s[6:7], v16, v16, v[16:17]
	v_or_b32_e32 v0, v12, v7
	v_mul_lo_u32 v0, v0, s50
	v_and_b32_e32 v3, 48, v11
	v_add3_u32 v8, 0, v0, v3
	v_lshl_add_u32 v9, v2, 3, v7
	v_add_u32_e32 v6, s2, v3
	v_cmp_gt_i32_e32 vcc, v1, v16
	v_cmp_le_i32_e64 s[8:9], v1, v16
	v_lshlrev_b32_e32 v10, 4, v1
	v_mov_b32_e32 v0, 0
	v_mov_b32_e32 v2, 0
	v_mov_b32_e32 v3, 0
	v_mov_b32_e32 v4, 0
	s_and_saveexec_b64 s[6:7], s[8:9]
	s_cbranch_execz .LBB0_1581
	v_add_u32_e32 v2, v9, v10
	v_mad_u64_u32 v[14:15], s[8:9], v2, s50, v[6:7]
	ds_read_b128 v[2:5], v8 offset:34816
	ds_read_b128 v[98:101], v14
	s_waitcnt lgkmcnt(0)
	v_mfma_f32_16x16x32_bf16 v[2:5], v[2:5], v[98:101], 0
	ds_read_b128 v[98:101], v8 offset:34880
	ds_read_b128 v[102:105], v14 offset:64
	s_waitcnt lgkmcnt(0)
	v_mfma_f32_16x16x32_bf16 v[2:5], v[98:101], v[102:105], v[2:5]
	ds_read_b128 v[98:101], v8 offset:34944
	ds_read_b128 v[102:105], v14 offset:128
	s_waitcnt lgkmcnt(0)
	v_mfma_f32_16x16x32_bf16 v[2:5], v[98:101], v[102:105], v[2:5]
	ds_read_b128 v[98:101], v8 offset:35008
	ds_read_b128 v[102:105], v14 offset:192
	s_waitcnt lgkmcnt(0)
	v_mfma_f32_16x16x32_bf16 v[2:5], v[98:101], v[102:105], v[2:5]

.LBB0_1647:
	s_or_b64 exec, exec, s[6:7]
	v_readlane_b32 s2, v253, 34
	v_readlane_b32 s3, v253, 35
	v_lshlrev_b32_e32 v2, 4, v42
	v_and_b32_e32 v166, 0xf0, v2
	s_waitcnt vmcnt(0)
	v_lshl_add_u64 v[0:1], v[16:17], 0, s[2:3]
	v_lshl_add_u64 v[0:1], v[0:1], 0, v[166:167]
	s_mov_b64 s[2:3], 0x264c2800
	v_ashrrev_i32_e32 v7, 4, v42
	v_lshl_add_u64 v[4:5], v[0:1], 0, s[2:3]
	v_lshlrev_b32_e32 v0, 7, v7
	v_ashrrev_i32_e32 v1, 31, v0
	v_lshl_add_u64 v[0:1], v[0:1], 1, v[4:5]
	s_waitcnt lgkmcnt(0)
	s_barrier
	global_load_dwordx4 v[44:47], v[0:1], off
	v_add_u32_e32 v6, 0, v166
	v_mad_u64_u32 v[132:133], s[6:7], v7, s50, v[6:7]
	v_lshlrev_b32_e32 v12, 4, v18
	v_readlane_b32 s2, v254, 45
	v_add_u32_e32 v0, 0x200, v42
	v_ashrrev_i32_e32 v7, 4, v0
	v_lshlrev_b32_e32 v0, 7, v7
	v_ashrrev_i32_e32 v1, 31, v0
	v_lshl_add_u64 v[0:1], v[0:1], 1, v[4:5]
	global_load_dwordx4 v[48:51], v[0:1], off
	v_mad_u64_u32 v[134:135], s[6:7], v7, s50, v[6:7]
	v_add_u32_e32 v0, 0x400, v42
	v_ashrrev_i32_e32 v7, 4, v0
	v_lshlrev_b32_e32 v0, 7, v7
	v_ashrrev_i32_e32 v1, 31, v0
	v_lshl_add_u64 v[0:1], v[0:1], 1, v[4:5]
	global_load_dwordx4 v[52:55], v[0:1], off
	v_mad_u64_u32 v[136:137], s[6:7], v7, s50, v[6:7]
	v_add_u32_e32 v0, 0x600, v42
	v_ashrrev_i32_e32 v7, 4, v0
	v_lshlrev_b32_e32 v0, 7, v7
	v_ashrrev_i32_e32 v1, 31, v0
	v_lshl_add_u64 v[0:1], v[0:1], 1, v[4:5]
	global_load_dwordx4 v[56:59], v[0:1], off
	v_mad_u64_u32 v[4:5], s[6:7], v7, s50, v[6:7]
	v_and_b32_e32 v7, 15, v42
	v_mov_b32_e32 v5, 0
	s_waitcnt vmcnt(0)
	ds_write_b128 v132, v[44:47]
	ds_write_b128 v134, v[48:51]
	ds_write_b128 v136, v[52:55]
	ds_write_b128 v4, v[56:59]
	v_lshlrev_b32_e32 v0, 1, v33
	v_and_b32_e32 v1, 2, v0
	v_mad_u64_u32 v[2:3], s[6:7], v18, v18, v[18:19]
	v_or_b32_e32 v0, v12, v7
	v_mul_lo_u32 v0, v0, s50
	v_and_b32_e32 v3, 48, v11
	v_add3_u32 v8, 0, v0, v3
	v_lshl_add_u32 v9, v2, 3, v7
	v_add_u32_e32 v6, s2, v3
	v_cmp_gt_i32_e32 vcc, v1, v18
	v_cmp_le_i32_e64 s[8:9], v1, v18
	v_lshlrev_b32_e32 v10, 4, v1
	v_mov_b32_e32 v0, 0
	v_mov_b32_e32 v2, 0
	v_mov_b32_e32 v3, 0
	v_mov_b32_e32 v4, 0
	s_and_saveexec_b64 s[6:7], s[8:9]
	s_cbranch_execz .LBB0_1649
	v_add_u32_e32 v2, v9, v10
	v_mad_u64_u32 v[14:15], s[8:9], v2, s50, v[6:7]
	ds_read_b128 v[2:5], v8 offset:34816
	ds_read_b128 v[44:47], v14
	s_waitcnt lgkmcnt(0)
	v_mfma_f32_16x16x32_bf16 v[2:5], v[2:5], v[44:47], 0
	ds_read_b128 v[44:47], v8 offset:34880
	ds_read_b128 v[48:51], v14 offset:64
	s_waitcnt lgkmcnt(0)
	v_mfma_f32_16x16x32_bf16 v[2:5], v[44:47], v[48:51], v[2:5]
	ds_read_b128 v[44:47], v8 offset:34944
	ds_read_b128 v[48:51], v14 offset:128
	s_waitcnt lgkmcnt(0)
	v_mfma_f32_16x16x32_bf16 v[2:5], v[44:47], v[48:51], v[2:5]
	ds_read_b128 v[44:47], v8 offset:35008
	ds_read_b128 v[48:51], v14 offset:192
	s_waitcnt lgkmcnt(0)
	v_mfma_f32_16x16x32_bf16 v[2:5], v[44:47], v[48:51], v[2:5]
